# S5 operator set-up co-scheduled with the memory-bound prologue: one item per workgroup in P0 (half before, half after the weight transposition)
# speedup vs baseline: 1.0044x; 1.0044x over previous
.LBB0_27:
	s_or_b64 exec, exec, s[6:7]
	s_and_b32 s98, s2, 8
	s_cmp_lg_u32 s98, 0
	s_cbranch_scc1 .Lssa_skip
	v_and_b32_e32 v210, 63, v208

.Lssa_448:
	s_mov_b64 s[4:5], -1
	s_barrier

.Lssa_exit:
	v_readfirstlane_b32 s79, v208
	s_getreg_b32 s60, hwreg(HW_REG_XCC_ID, 0, 4)
	v_cmp_gt_u32_e64 s[4:5], 32, v208
.Lssa_skip:
	s_lshr_b32 s96, s79, 6
	s_cmp_lt_i32 s3, 1
	s_cselect_b64 s[6:7], -1, 0
	s_cmp_gt_i32 s89, 0
	s_cselect_b64 s[8:9], -1, 0
	s_and_b64 s[24:25], s[6:7], s[8:9]
	s_andn2_b64 vcc, exec, s[24:25]
	v_and_b32_e32 v210, 63, v208
	s_cbranch_vccnz .LBB0_114
	s_lshl_b32 s6, s93, 3
	s_add_i32 s36, s6, s96
	s_lshl_b32 s38, s28, 3
	s_mov_b64 s[12:13], s[0:1]
	s_cmpk_gt_i32 s36, 0x2dff
	s_cbranch_scc1 .LBB0_91
	s_load_dwordx4 s[8:11], s[12:13], 0x8
	s_load_dwordx2 s[6:7], s[12:13], 0x18
	s_load_dwordx2 s[16:17], s[12:13], 0xa8
	v_lshlrev_b32_e32 v0, 3, v208
	v_and_b32_e32 v0, 56, v0
	s_lshl_b32 s14, s96, 14
	v_lshrrev_b32_e32 v59, 3, v210
	v_mul_u32_u24_e32 v4, 0x84, v0
	v_lshlrev_b32_e32 v0, 1, v0
	v_mov_b32_e32 v1, 0
	s_add_i32 s18, s14, 0
	s_waitcnt lgkmcnt(0)
	v_lshl_add_u64 v[16:17], s[16:17], 0, v[0:1]
	v_lshlrev_b32_e32 v0, 2, v59
	v_add3_u32 v60, s18, v4, v0
	s_mov_b64 s[18:19], 0xc00000
	s_mov_b64 s[16:17], 0x400000
	v_lshl_add_u64 v[6:7], v[16:17], 0, s[18:19]
	s_mov_b64 s[18:19], 0x1400000
	v_lshl_add_u64 v[2:3], v[16:17], 0, s[16:17]
	s_mov_b64 s[16:17], 0xa00000
	s_cmp_lg_u64 s[10:11], 0
	v_lshl_add_u64 v[8:9], v[16:17], 0, s[18:19]
	s_mov_b64 s[18:19], 0x2c00000
	v_lshl_add_u64 v[4:5], v[16:17], 0, s[16:17]
	s_cselect_b64 s[16:17], -1, 0
	s_add_u32 s8, s8, 0x1000
	v_lshl_add_u64 v[10:11], v[16:17], 0, s[18:19]
	s_mov_b64 s[18:19], 0x2e00000
	v_and_b32_e32 v18, 31, v208
	s_addc_u32 s9, s9, 0
	v_lshl_add_u64 v[12:13], v[16:17], 0, s[18:19]
	s_mov_b64 s[18:19], 0x2400000
	v_lshl_add_u64 v[14:15], v[16:17], 0, s[18:19]
	s_add_u32 s18, s10, 0x1000
	v_lshlrev_b32_e32 v18, 2, v18
	v_mov_b32_e32 v19, v1
	v_lshrrev_b32_e32 v58, 5, v210
	s_addc_u32 s19, s11, 0
	v_lshl_add_u64 v[20:21], s[6:7], 0, v[18:19]
	s_lshl_b32 s6, s93, 8
	s_lshl_b32 s7, s96, 5
	v_mul_u32_u24_e32 v0, 0x84, v58
	s_add_i32 s37, s6, s7
	s_lshl_b32 s6, s93, 4
	s_lshl_b32 s7, s96, 1
	v_or_b32_e32 v0, s14, v0
	s_add_i32 s6, s6, s7
	s_lshl_b32 s7, s93, 11
	s_lshl_b32 s14, s96, 8
	s_mov_b64 s[20:21], 0x1c00000
	s_add_i32 s47, s7, s14
	s_lshl_b32 s7, s93, 7
	s_lshl_b32 s14, s96, 4
	s_mov_b32 s15, 0
	v_or_b32_e32 v61, 8, v59
	v_or_b32_e32 v62, 16, v59
	v_or_b32_e32 v63, 24, v59
	v_lshl_add_u64 v[16:17], v[16:17], 0, s[20:21]
	v_add3_u32 v64, v0, v18, 0
	v_or_b32_e32 v65, 14, v58
	v_or_b32_e32 v66, 12, v58
	v_or_b32_e32 v67, 10, v58
	v_or_b32_e32 v68, 8, v58
	v_or_b32_e32 v69, 6, v58
	v_or_b32_e32 v70, 4, v58
	v_or_b32_e32 v71, 2, v58
	s_lshl_b32 s39, s28, 8
	s_add_i32 s42, s6, 0x1b400
	s_lshl_b32 s43, s28, 4
	s_add_i32 s44, s36, 0xe200
	v_lshlrev_b32_e32 v22, 2, v58
	v_mov_b32_e32 v23, v1
	s_add_i32 s45, s6, 0x1d400
	s_add_i32 s46, s6, 0x1d800
	s_lshl_b32 s48, s28, 11
	s_add_i32 s49, s7, s14
	s_lshl_b32 s50, s28, 7
	s_add_i32 s51, s36, 0xf000
	v_or_b32_e32 v24, 0x1000000, v18
	v_mov_b32_e32 v25, v1
	s_add_i32 s52, s6, 0x1f000
	s_movk_i32 s53, 0x3040
	s_mov_b32 s54, s36
	s_branch .LBB0_31

.LBB0_91:
	s_and_b32 s98, s2, 8
	s_cmp_eq_u32 s98, 0
	s_cbranch_scc1 .Lssc_skip

.Lssc_exit:
	v_readfirstlane_b32 s79, v208
	s_getreg_b32 s60, hwreg(HW_REG_XCC_ID, 0, 4)
	v_cmp_gt_u32_e64 s[4:5], 32, v208
	s_lshr_b32 s96, s79, 6
	s_cmp_lt_i32 s3, 1
	s_cselect_b64 s[6:7], -1, 0
	s_cmp_gt_i32 s89, 0
	s_cselect_b64 s[8:9], -1, 0
	s_and_b64 s[24:25], s[6:7], s[8:9]
	s_lshl_b32 s6, s93, 3
	s_add_i32 s36, s6, s96
	s_lshl_b32 s38, s28, 3
